# v26 + RG-LRU causal-conv: weight ds_reads double-buffered one tap ahead (same FMA order)
# baseline (speedup 1.0000x reference)
; #define LAS __attribute__((address_space(3)))
; __device__ __forceinline__ float bflo(unsigned w) { return __uint_as_float(w << 16); }
; __device__ __forceinline__ float bfhi(unsigned w) { return __uint_as_float(w & 0xffff0000u); }
; __device__ __forceinline__ u32x4 pack8(f32x4 a, f32x4 b) { u32x4 w; w.x = cvtpk(a[0], a[1]); w.y = cvtpk(a[2], a[3]); w.z = cvtpk(b[0], b[1]); w.w = cvtpk(b[2], b[3]); return w; }
; __device__ __forceinline__ void lru_load_rows(const Params& P, int l, int tile, int r0, int c0, u32x4 (&xr)[2][4]) {
;     ...
; #pragma unroll
;     for (int j = 0; j < 2; ++j) {
;         const int m = tile * 64 + r0 + 32 * j;
;         const int pos = samp ? ((m - NPT) & 3) : (m % LP);
; #pragma unroll
;         for (int i = 0; i < 4; ++i) {
;             u32x4 v = {0u, 0u, 0u, 0u};
;             if (pos - i >= 0) v = *(const u32x4*)(XR + (size_t)(m - i) * 1024 + c0);
; template <int MODE> __device__ __forceinline__ void lru_phase(const Params& P, LAS unsigned char* lds, int l, int tid_in) {
;     ...
;         if (cur) {
; #pragma unroll
;             for (int j = 0; j < 2; ++j) {
;                 f32x4 a0 = *(const LAS f32x4*)(cwl + 512 + c8 * 8), a1 = *(const LAS f32x4*)(cwl + 512 + c8 * 8 + 4);
; #pragma unroll
;                 for (int i = 0; i < 4; ++i) { const u32x4 xw = xr[j][i]; f32x4 x0, x1; const f32x4 w0 = *(const LAS f32x4*)(cwl + i * 128 + c8 * 8), w1 = *(const LAS f32x4*)(cwl + i * 128 + c8 * 8 + 4);
;                     x0[0] = bflo(xw.x); x0[1] = bfhi(xw.x); x0[2] = bflo(xw.y); x0[3] = bfhi(xw.y); x1[0] = bflo(xw.z); x1[1] = bfhi(xw.z); x1[2] = bflo(xw.w); x1[3] = bfhi(xw.w);
;                     a0 += w0 * x0; a1 += w1 * x1; }
;                 *(LAS u32x4*)(xcb + (r0 + 32 * j) * 136 + c8 * 8) = pack8(a0, a1);
;             }
;             if (tile + tstride < NTILE64) lru_load_rows(P, l, tile + tstride, r0, c0, xr);
.LBB0_1105:
	s_cmpk_lt_u32 s42, 0x10a
	s_cselect_b64 s[4:5], -1, 0
	s_cmp_gt_i32 s12, -1
	s_cselect_b64 s[54:55], -1, 0
	s_or_b64 s[0:1], s[54:55], s[4:5]
	v_cndmask_b32_e64 v0, 0, 1, s[0:1]
	v_cmp_ne_u32_e64 s[46:47], 1, v0
	s_andn2_b64 vcc, exec, s[0:1]
	s_cbranch_vccnz .LBB0_1113
	v_cndmask_b32_e64 v0, 0, 1, s[4:5]
	v_cmp_ne_u32_e64 s[48:49], 1, v0
	s_andn2_b64 vcc, exec, s[4:5]
	s_lshl_b32 s43, s42, 6
	s_cbranch_vccnz .LBB0_1159
	ds_read_b128 v[0:3], v182
	ds_read_b128 v[4:7], v182 offset:16
	ds_read_b128 v[8:11], v183
	ds_read_b128 v[12:15], v183 offset:16
	ds_read_b128 v[24:27], v183 offset:512
	ds_read_b128 v[28:31], v183 offset:528
	s_waitcnt vmcnt(2)
	v_lshlrev_b32_e32 v16, 16, v120
	v_and_b32_e32 v17, 0xffff0000, v120
	v_lshlrev_b32_e32 v18, 16, v121
	v_and_b32_e32 v19, 0xffff0000, v121
	v_lshlrev_b32_e32 v20, 16, v122
	v_and_b32_e32 v21, 0xffff0000, v122
	v_lshlrev_b32_e32 v22, 16, v123
	v_and_b32_e32 v23, 0xffff0000, v123
	s_waitcnt lgkmcnt(2)
	v_pk_fma_f32 v[8:9], v[8:9], v[16:17], v[0:1]
	v_pk_fma_f32 v[10:11], v[10:11], v[18:19], v[2:3]
	v_pk_fma_f32 v[12:13], v[12:13], v[20:21], v[4:5]
	v_pk_fma_f32 v[14:15], v[14:15], v[22:23], v[6:7]
	ds_read_b128 v[0:3], v183 offset:1024
	ds_read_b128 v[4:7], v183 offset:1040
	v_lshlrev_b32_e32 v16, 16, v124
	v_and_b32_e32 v17, 0xffff0000, v124
	v_lshlrev_b32_e32 v18, 16, v125
	v_and_b32_e32 v19, 0xffff0000, v125
	v_lshlrev_b32_e32 v20, 16, v126
	v_and_b32_e32 v21, 0xffff0000, v126
	v_lshlrev_b32_e32 v22, 16, v127
	v_and_b32_e32 v23, 0xffff0000, v127
	s_waitcnt lgkmcnt(2)
	v_pk_fma_f32 v[10:11], v[26:27], v[18:19], v[10:11]
	v_pk_fma_f32 v[8:9], v[24:25], v[16:17], v[8:9]
	v_pk_fma_f32 v[14:15], v[30:31], v[22:23], v[14:15]
	v_pk_fma_f32 v[12:13], v[28:29], v[20:21], v[12:13]
	ds_read_b128 v[24:27], v183 offset:1536
	ds_read_b128 v[28:31], v183 offset:1552
	v_lshlrev_b32_e32 v16, 16, v128
	v_and_b32_e32 v17, 0xffff0000, v128
	v_lshlrev_b32_e32 v18, 16, v129
	v_and_b32_e32 v19, 0xffff0000, v129
	v_lshlrev_b32_e32 v20, 16, v130
	v_and_b32_e32 v21, 0xffff0000, v130
	v_lshlrev_b32_e32 v22, 16, v131
	v_and_b32_e32 v23, 0xffff0000, v131
	s_waitcnt lgkmcnt(2)
	v_pk_fma_f32 v[8:9], v[0:1], v[16:17], v[8:9]
	v_pk_fma_f32 v[10:11], v[2:3], v[18:19], v[10:11]
	v_pk_fma_f32 v[12:13], v[4:5], v[20:21], v[12:13]
	v_pk_fma_f32 v[14:15], v[6:7], v[22:23], v[14:15]
	v_lshlrev_b32_e32 v16, 16, v132
	v_and_b32_e32 v17, 0xffff0000, v132
	v_lshlrev_b32_e32 v18, 16, v133
	v_and_b32_e32 v19, 0xffff0000, v133
	v_lshlrev_b32_e32 v20, 16, v134
	v_and_b32_e32 v21, 0xffff0000, v134
	v_lshlrev_b32_e32 v22, 16, v135
	v_and_b32_e32 v23, 0xffff0000, v135
	s_waitcnt lgkmcnt(0)
	v_pk_fma_f32 v[2:3], v[26:27], v[18:19], v[10:11]
	v_pk_fma_f32 v[0:1], v[24:25], v[16:17], v[8:9]
	v_pk_fma_f32 v[6:7], v[30:31], v[22:23], v[14:15]
	v_pk_fma_f32 v[4:5], v[28:29], v[20:21], v[12:13]
	v_cvt_pk_bf16_f32 v0, v0, v1
	v_cvt_pk_bf16_f32 v1, v2, v3
	v_cvt_pk_bf16_f32 v2, v4, v5
	v_cvt_pk_bf16_f32 v3, v6, v7
	ds_write_b128 v238, v[0:3]
	ds_read_b128 v[0:3], v182
	ds_read_b128 v[4:7], v182 offset:16
	ds_read_b128 v[8:11], v183
	ds_read_b128 v[12:15], v183 offset:16
	ds_read_b128 v[24:27], v183 offset:512
	ds_read_b128 v[28:31], v183 offset:528
	v_lshlrev_b32_e32 v16, 16, v136
	v_and_b32_e32 v17, 0xffff0000, v136
	v_lshlrev_b32_e32 v18, 16, v137
	v_and_b32_e32 v19, 0xffff0000, v137
	v_lshlrev_b32_e32 v20, 16, v138
	v_and_b32_e32 v21, 0xffff0000, v138
	v_lshlrev_b32_e32 v22, 16, v139
	v_and_b32_e32 v23, 0xffff0000, v139
	s_waitcnt lgkmcnt(2)
	v_pk_fma_f32 v[8:9], v[8:9], v[16:17], v[0:1]
	v_pk_fma_f32 v[10:11], v[10:11], v[18:19], v[2:3]
	v_pk_fma_f32 v[12:13], v[12:13], v[20:21], v[4:5]
	v_pk_fma_f32 v[14:15], v[14:15], v[22:23], v[6:7]
	ds_read_b128 v[0:3], v183 offset:1024
	ds_read_b128 v[4:7], v183 offset:1040
	v_lshlrev_b32_e32 v16, 16, v140
	v_and_b32_e32 v17, 0xffff0000, v140
	v_lshlrev_b32_e32 v18, 16, v141
	v_and_b32_e32 v19, 0xffff0000, v141
	v_lshlrev_b32_e32 v20, 16, v142
	v_and_b32_e32 v21, 0xffff0000, v142
	v_lshlrev_b32_e32 v22, 16, v143
	v_and_b32_e32 v23, 0xffff0000, v143
	s_waitcnt lgkmcnt(2)
	v_pk_fma_f32 v[10:11], v[26:27], v[18:19], v[10:11]
	v_pk_fma_f32 v[8:9], v[24:25], v[16:17], v[8:9]
	v_pk_fma_f32 v[14:15], v[30:31], v[22:23], v[14:15]
	v_pk_fma_f32 v[12:13], v[28:29], v[20:21], v[12:13]
	ds_read_b128 v[24:27], v183 offset:1536
	ds_read_b128 v[28:31], v183 offset:1552
	v_lshlrev_b32_e32 v16, 16, v144
	v_and_b32_e32 v17, 0xffff0000, v144
	v_lshlrev_b32_e32 v18, 16, v145
	v_and_b32_e32 v19, 0xffff0000, v145
	v_lshlrev_b32_e32 v20, 16, v146
	v_and_b32_e32 v21, 0xffff0000, v146
	v_lshlrev_b32_e32 v22, 16, v147
	v_and_b32_e32 v23, 0xffff0000, v147
	s_waitcnt lgkmcnt(2)
	v_pk_fma_f32 v[8:9], v[0:1], v[16:17], v[8:9]
	v_pk_fma_f32 v[10:11], v[2:3], v[18:19], v[10:11]
	v_pk_fma_f32 v[12:13], v[4:5], v[20:21], v[12:13]
	v_pk_fma_f32 v[14:15], v[6:7], v[22:23], v[14:15]
	v_lshlrev_b32_e32 v16, 16, v148
	v_and_b32_e32 v17, 0xffff0000, v148
	v_lshlrev_b32_e32 v18, 16, v149
	v_and_b32_e32 v19, 0xffff0000, v149
	v_lshlrev_b32_e32 v20, 16, v150
	v_and_b32_e32 v21, 0xffff0000, v150
	v_lshlrev_b32_e32 v22, 16, v151
	v_and_b32_e32 v23, 0xffff0000, v151
	s_waitcnt lgkmcnt(0)
	v_pk_fma_f32 v[2:3], v[26:27], v[18:19], v[10:11]
	v_pk_fma_f32 v[0:1], v[24:25], v[16:17], v[8:9]
	v_pk_fma_f32 v[6:7], v[30:31], v[22:23], v[14:15]
	v_pk_fma_f32 v[4:5], v[28:29], v[20:21], v[12:13]
	v_cvt_pk_bf16_f32 v0, v0, v1
	v_cvt_pk_bf16_f32 v1, v2, v3
	v_cvt_pk_bf16_f32 v2, v4, v5
	v_cvt_pk_bf16_f32 v3, v6, v7
	v_readlane_b32 s0, v255, 32
	s_nop 0
	s_add_i32 s0, s42, s0
	s_cmpk_gt_u32 s0, 0x109
	ds_write_b128 v238, v[0:3] offset:8704
	s_cbranch_scc1 .LBB0_1158
	v_lshl_add_u32 v0, s0, 6, v177
	v_mul_hi_i32 v1, v0, s71
	v_lshrrev_b32_e32 v2, 31, v1
	v_ashrrev_i32_e32 v1, 7, v1
	v_add_u32_e32 v1, v1, v2
	s_cmpk_gt_u32 s0, 0x101
	v_mul_lo_u32 v1, v1, s73
	v_sub_u32_e32 v1, v0, v1
	s_cselect_b64 s[52:53], -1, 0
	v_cndmask_b32_e64 v4, v1, v154, s[52:53]
	v_cmp_lt_i32_e32 vcc, -1, v4
	v_ashrrev_i32_e32 v1, 31, v0
	s_and_saveexec_b64 s[0:1], vcc
	s_xor_b64 s[0:1], exec, s[0:1]
	s_cbranch_execz .LBB0_1110
	v_lshlrev_b64 v[2:3], 11, v[0:1]
	v_lshl_add_u64 v[2:3], v[168:169], 0, v[2:3]
	global_load_dwordx4 v[120:123], v[2:3], off
